# stack with P8 merge GEMM final epilogue gate loads hoisted (no early sample-unit loads)
# baseline (speedup 1.0000x reference)
; __device__ __forceinline__ unsigned cvt_pk_bf16(float lo, float hi) { unsigned r; asm volatile("v_cvt_pk_bf16_f32 %0, %1, %2" : "=v"(r) : "v"(lo), "v"(hi)); return r; }
; __device__ __forceinline__ void unpack8(u32x4 w, f32x4& lo, f32x4& hi) { lo = (f32x4){bfl(w.x), bfh(w.x), bfl(w.y), bfh(w.y)}; hi = (f32x4){bfl(w.z), bfh(w.z), bfl(w.w), bfh(w.w)}; }
;     __device__ __forceinline__ void operator()(const f32x4 (&acc)[2][2][4][2], const Unit& u, int wr, int wc, int fr, int fq) const {
;         const int row0 = u.pm * BM + wr * 64 + fr, col0 = u.pn * BM + wc * 32 + 8 * fq;
; #pragma unroll
;         for (int ai = 0; ai < 2; ++ai)
; #pragma unroll
;             for (int m = 0; m < 4; ++m) { const size_t ro = (size_t)(row0 + ai * HALF + m * 16) * D + col0;
; #pragma unroll
;                 for (int bj = 0; bj < 2; ++bj) { const u32x4 bw = *(const u32x4*)(GB + ro + bj * HALF); f32x4 b0, b1; unpack8(bw, b0, b1);
;                     f32x4 v0 = acc[ai][bj][m][0], v1 = acc[ai][bj][m][1];
; #pragma unroll
;                     for (int e = 0; e < 4; ++e) { v0[e] *= fmaxf(b0[e], 1e-20f); v1[e] *= fmaxf(b1[e], 1e-20f); }
;                     u32x4 w; w.x = cvt_pk_bf16(v0[0], v0[1]); w.y = cvt_pk_bf16(v0[2], v0[3]); w.z = cvt_pk_bf16(v1[0], v1[1]); w.w = cvt_pk_bf16(v1[2], v1[3]);
;                     *(u32x4*)(MIX + ro + bj * HALF) = w; }
;                 asm volatile("" ::: "memory"); }
.LBB0_1204:
	s_mov_b64 s[28:29], 0x80000
	s_andn2_b64 vcc, exec, s[0:1]
	s_mov_b64 s[0:1], -1
	v_lshl_add_u32 v134, s26, 8, v160
	v_or_b32_e32 v132, s19, v163
	v_lshl_add_u32 v240, v134, 11, v132
	v_lshlrev_b32_e32 v130, 1, v240
	v_add_u32_e32 v131, 0x10000, v130
	v_add_u32_e32 v132, 0x20000, v130
	v_add_u32_e32 v133, 0x30000, v130
	v_add_u32_e32 v134, 0x80000, v130
	v_add_u32_e32 v135, 0x90000, v130
	v_add_u32_e32 v136, 0xa0000, v130
	v_add_u32_e32 v137, 0xb0000, v130
	global_load_dwordx4 v[166:169], v130, s[8:9] offset:0
	global_load_dwordx4 v[170:173], v130, s[8:9] offset:256
	global_load_dwordx4 v[174:177], v131, s[8:9] offset:0
	global_load_dwordx4 v[178:181], v131, s[8:9] offset:256
	global_load_dwordx4 v[182:185], v132, s[8:9] offset:0
	global_load_dwordx4 v[186:189], v132, s[8:9] offset:256
	global_load_dwordx4 v[190:193], v133, s[8:9] offset:0
	global_load_dwordx4 v[194:197], v133, s[8:9] offset:256
	global_load_dwordx4 v[198:201], v134, s[8:9] offset:0
	global_load_dwordx4 v[202:205], v134, s[8:9] offset:256
	global_load_dwordx4 v[206:209], v135, s[8:9] offset:0
	global_load_dwordx4 v[210:213], v135, s[8:9] offset:256
	global_load_dwordx4 v[214:217], v136, s[8:9] offset:0
	global_load_dwordx4 v[218:221], v136, s[8:9] offset:256
	global_load_dwordx4 v[222:225], v137, s[8:9] offset:0
	global_load_dwordx4 v[226:229], v137, s[8:9] offset:256
	s_waitcnt vmcnt(15)
	v_lshlrev_b32_e32 v230, 16, v166
	v_and_b32_e32 v231, 0xffff0000, v166
	v_lshlrev_b32_e32 v232, 16, v167
	v_and_b32_e32 v233, 0xffff0000, v167
	v_lshlrev_b32_e32 v234, 16, v168
	v_and_b32_e32 v235, 0xffff0000, v168
	v_lshlrev_b32_e32 v236, 16, v169
	v_and_b32_e32 v237, 0xffff0000, v169
	v_max_f32_e32 v230, v230, v230
	v_max_f32_e32 v231, v231, v231
	v_max_f32_e32 v232, v232, v232
	v_max_f32_e32 v233, v233, v233
	v_max_f32_e32 v234, v234, v234
	v_max_f32_e32 v235, v235, v235
	v_max_f32_e32 v236, v236, v236
	v_max_f32_e32 v237, v237, v237
	v_max_f32_e32 v230, 0x1e3ce508, v230
	v_max_f32_e32 v231, 0x1e3ce508, v231
	v_max_f32_e32 v232, 0x1e3ce508, v232
	v_max_f32_e32 v233, 0x1e3ce508, v233
	v_max_f32_e32 v234, 0x1e3ce508, v234
	v_max_f32_e32 v235, 0x1e3ce508, v235
	v_max_f32_e32 v236, 0x1e3ce508, v236
	v_max_f32_e32 v237, 0x1e3ce508, v237
	v_mul_f32_e32 v126, v126, v230
	v_mul_f32_e32 v127, v127, v231
	v_mul_f32_e32 v128, v128, v232
	v_mul_f32_e32 v129, v129, v233
	v_mul_f32_e32 v122, v122, v234
	v_mul_f32_e32 v123, v123, v235
	v_mul_f32_e32 v124, v124, v236
	v_mul_f32_e32 v125, v125, v237
	v_cvt_pk_bf16_f32 v238, v126, v127
	v_cvt_pk_bf16_f32 v239, v128, v129
	v_cvt_pk_bf16_f32 v240, v122, v123
	v_cvt_pk_bf16_f32 v241, v124, v125
	global_store_dwordx4 v130, v[238:241], s[12:13] offset:0
	s_waitcnt vmcnt(15)
	v_lshlrev_b32_e32 v230, 16, v170
	v_and_b32_e32 v231, 0xffff0000, v170
	v_lshlrev_b32_e32 v232, 16, v171
	v_and_b32_e32 v233, 0xffff0000, v171
	v_lshlrev_b32_e32 v234, 16, v172
	v_and_b32_e32 v235, 0xffff0000, v172
	v_lshlrev_b32_e32 v236, 16, v173
	v_and_b32_e32 v237, 0xffff0000, v173
	v_max_f32_e32 v230, v230, v230
	v_max_f32_e32 v231, v231, v231
	v_max_f32_e32 v232, v232, v232
	v_max_f32_e32 v233, v233, v233
	v_max_f32_e32 v234, v234, v234
	v_max_f32_e32 v235, v235, v235
	v_max_f32_e32 v236, v236, v236
	v_max_f32_e32 v237, v237, v237
	v_max_f32_e32 v230, 0x1e3ce508, v230
	v_max_f32_e32 v231, 0x1e3ce508, v231
	v_max_f32_e32 v232, 0x1e3ce508, v232
	v_max_f32_e32 v233, 0x1e3ce508, v233
	v_max_f32_e32 v234, 0x1e3ce508, v234
	v_max_f32_e32 v235, 0x1e3ce508, v235
	v_max_f32_e32 v236, 0x1e3ce508, v236
	v_max_f32_e32 v237, 0x1e3ce508, v237
	v_mul_f32_e32 v118, v118, v230
	v_mul_f32_e32 v119, v119, v231
	v_mul_f32_e32 v120, v120, v232
	v_mul_f32_e32 v121, v121, v233
	v_mul_f32_e32 v114, v114, v234
	v_mul_f32_e32 v115, v115, v235
	v_mul_f32_e32 v116, v116, v236
	v_mul_f32_e32 v117, v117, v237
	v_cvt_pk_bf16_f32 v238, v118, v119
	v_cvt_pk_bf16_f32 v239, v120, v121
	v_cvt_pk_bf16_f32 v240, v114, v115
	v_cvt_pk_bf16_f32 v241, v116, v117
	global_store_dwordx4 v130, v[238:241], s[12:13] offset:256
	s_waitcnt vmcnt(15)
	v_lshlrev_b32_e32 v230, 16, v174
	v_and_b32_e32 v231, 0xffff0000, v174
	v_lshlrev_b32_e32 v232, 16, v175
	v_and_b32_e32 v233, 0xffff0000, v175
	v_lshlrev_b32_e32 v234, 16, v176
	v_and_b32_e32 v235, 0xffff0000, v176
	v_lshlrev_b32_e32 v236, 16, v177
	v_and_b32_e32 v237, 0xffff0000, v177
	v_max_f32_e32 v230, v230, v230
	v_max_f32_e32 v231, v231, v231
	v_max_f32_e32 v232, v232, v232
	v_max_f32_e32 v233, v233, v233
	v_max_f32_e32 v234, v234, v234
	v_max_f32_e32 v235, v235, v235
	v_max_f32_e32 v236, v236, v236
	v_max_f32_e32 v237, v237, v237
	v_max_f32_e32 v230, 0x1e3ce508, v230
	v_max_f32_e32 v231, 0x1e3ce508, v231
	v_max_f32_e32 v232, 0x1e3ce508, v232
	v_max_f32_e32 v233, 0x1e3ce508, v233
	v_max_f32_e32 v234, 0x1e3ce508, v234
	v_max_f32_e32 v235, 0x1e3ce508, v235
	v_max_f32_e32 v236, 0x1e3ce508, v236
	v_max_f32_e32 v237, 0x1e3ce508, v237
	v_mul_f32_e32 v110, v110, v230
	v_mul_f32_e32 v111, v111, v231
	v_mul_f32_e32 v112, v112, v232
	v_mul_f32_e32 v113, v113, v233
	v_mul_f32_e32 v106, v106, v234
	v_mul_f32_e32 v107, v107, v235
	v_mul_f32_e32 v108, v108, v236
	v_mul_f32_e32 v109, v109, v237
	v_cvt_pk_bf16_f32 v238, v110, v111
	v_cvt_pk_bf16_f32 v239, v112, v113
	v_cvt_pk_bf16_f32 v240, v106, v107
	v_cvt_pk_bf16_f32 v241, v108, v109
	global_store_dwordx4 v131, v[238:241], s[12:13] offset:0
	s_waitcnt vmcnt(15)
; __device__ __forceinline__ unsigned cvt_pk_bf16(float lo, float hi) { unsigned r; asm volatile("v_cvt_pk_bf16_f32 %0, %1, %2" : "=v"(r) : "v"(lo), "v"(hi)); return r; }
; __device__ __forceinline__ void unpack8(u32x4 w, f32x4& lo, f32x4& hi) { lo = (f32x4){bfl(w.x), bfh(w.x), bfl(w.y), bfh(w.y)}; hi = (f32x4){bfl(w.z), bfh(w.z), bfl(w.w), bfh(w.w)}; }
;     __device__ __forceinline__ void operator()(const f32x4 (&acc)[2][2][4][2], const Unit& u, int wr, int wc, int fr, int fq) const {
;     ...
;             for (int m = 0; m < 4; ++m) { const size_t ro = (size_t)(row0 + ai * HALF + m * 16) * D + col0;
; #pragma unroll
;                 for (int bj = 0; bj < 2; ++bj) { const u32x4 bw = *(const u32x4*)(GB + ro + bj * HALF); f32x4 b0, b1; unpack8(bw, b0, b1);
;                     f32x4 v0 = acc[ai][bj][m][0], v1 = acc[ai][bj][m][1];
; #pragma unroll
;                     for (int e = 0; e < 4; ++e) { v0[e] *= fmaxf(b0[e], 1e-20f); v1[e] *= fmaxf(b1[e], 1e-20f); }
;                     u32x4 w; w.x = cvt_pk_bf16(v0[0], v0[1]); w.y = cvt_pk_bf16(v0[2], v0[3]); w.z = cvt_pk_bf16(v1[0], v1[1]); w.w = cvt_pk_bf16(v1[2], v1[3]);
;                     *(u32x4*)(MIX + ro + bj * HALF) = w; }
;                 asm volatile("" ::: "memory"); }
	v_lshlrev_b32_e32 v230, 16, v178
	v_and_b32_e32 v231, 0xffff0000, v178
	v_lshlrev_b32_e32 v232, 16, v179
	v_and_b32_e32 v233, 0xffff0000, v179
	v_lshlrev_b32_e32 v234, 16, v180
	v_and_b32_e32 v235, 0xffff0000, v180
	v_lshlrev_b32_e32 v236, 16, v181
	v_and_b32_e32 v237, 0xffff0000, v181
	v_max_f32_e32 v230, v230, v230
	v_max_f32_e32 v231, v231, v231
	v_max_f32_e32 v232, v232, v232
	v_max_f32_e32 v233, v233, v233
	v_max_f32_e32 v234, v234, v234
	v_max_f32_e32 v235, v235, v235
	v_max_f32_e32 v236, v236, v236
	v_max_f32_e32 v237, v237, v237
	v_max_f32_e32 v230, 0x1e3ce508, v230
	v_max_f32_e32 v231, 0x1e3ce508, v231
	v_max_f32_e32 v232, 0x1e3ce508, v232
	v_max_f32_e32 v233, 0x1e3ce508, v233
	v_max_f32_e32 v234, 0x1e3ce508, v234
	v_max_f32_e32 v235, 0x1e3ce508, v235
	v_max_f32_e32 v236, 0x1e3ce508, v236
	v_max_f32_e32 v237, 0x1e3ce508, v237
	v_mul_f32_e32 v102, v102, v230
	v_mul_f32_e32 v103, v103, v231
	v_mul_f32_e32 v104, v104, v232
	v_mul_f32_e32 v105, v105, v233
	v_mul_f32_e32 v98, v98, v234
	v_mul_f32_e32 v99, v99, v235
	v_mul_f32_e32 v100, v100, v236
	v_mul_f32_e32 v101, v101, v237
	v_cvt_pk_bf16_f32 v238, v102, v103
	v_cvt_pk_bf16_f32 v239, v104, v105
	v_cvt_pk_bf16_f32 v240, v98, v99
	v_cvt_pk_bf16_f32 v241, v100, v101
	global_store_dwordx4 v131, v[238:241], s[12:13] offset:256
	s_waitcnt vmcnt(15)
	v_lshlrev_b32_e32 v230, 16, v182
	v_and_b32_e32 v231, 0xffff0000, v182
	v_lshlrev_b32_e32 v232, 16, v183
	v_and_b32_e32 v233, 0xffff0000, v183
	v_lshlrev_b32_e32 v234, 16, v184
	v_and_b32_e32 v235, 0xffff0000, v184
	v_lshlrev_b32_e32 v236, 16, v185
	v_and_b32_e32 v237, 0xffff0000, v185
	v_max_f32_e32 v230, v230, v230
	v_max_f32_e32 v231, v231, v231
	v_max_f32_e32 v232, v232, v232
	v_max_f32_e32 v233, v233, v233
	v_max_f32_e32 v234, v234, v234
	v_max_f32_e32 v235, v235, v235
	v_max_f32_e32 v236, v236, v236
	v_max_f32_e32 v237, v237, v237
	v_max_f32_e32 v230, 0x1e3ce508, v230
	v_max_f32_e32 v231, 0x1e3ce508, v231
	v_max_f32_e32 v232, 0x1e3ce508, v232
	v_max_f32_e32 v233, 0x1e3ce508, v233
	v_max_f32_e32 v234, 0x1e3ce508, v234
	v_max_f32_e32 v235, 0x1e3ce508, v235
	v_max_f32_e32 v236, 0x1e3ce508, v236
	v_max_f32_e32 v237, 0x1e3ce508, v237
	v_mul_f32_e32 v94, v94, v230
	v_mul_f32_e32 v95, v95, v231
	v_mul_f32_e32 v96, v96, v232
	v_mul_f32_e32 v97, v97, v233
	v_mul_f32_e32 v90, v90, v234
	v_mul_f32_e32 v91, v91, v235
	v_mul_f32_e32 v92, v92, v236
	v_mul_f32_e32 v93, v93, v237
	v_cvt_pk_bf16_f32 v238, v94, v95
	v_cvt_pk_bf16_f32 v239, v96, v97
	v_cvt_pk_bf16_f32 v240, v90, v91
	v_cvt_pk_bf16_f32 v241, v92, v93
	global_store_dwordx4 v132, v[238:241], s[12:13] offset:0
	s_waitcnt vmcnt(15)
	v_lshlrev_b32_e32 v230, 16, v186
	v_and_b32_e32 v231, 0xffff0000, v186
	v_lshlrev_b32_e32 v232, 16, v187
	v_and_b32_e32 v233, 0xffff0000, v187
	v_lshlrev_b32_e32 v234, 16, v188
	v_and_b32_e32 v235, 0xffff0000, v188
	v_lshlrev_b32_e32 v236, 16, v189
	v_and_b32_e32 v237, 0xffff0000, v189
	v_max_f32_e32 v230, v230, v230
	v_max_f32_e32 v231, v231, v231
	v_max_f32_e32 v232, v232, v232
	v_max_f32_e32 v233, v233, v233
	v_max_f32_e32 v234, v234, v234
	v_max_f32_e32 v235, v235, v235
	v_max_f32_e32 v236, v236, v236
	v_max_f32_e32 v237, v237, v237
	v_max_f32_e32 v230, 0x1e3ce508, v230
	v_max_f32_e32 v231, 0x1e3ce508, v231
	v_max_f32_e32 v232, 0x1e3ce508, v232
	v_max_f32_e32 v233, 0x1e3ce508, v233
	v_max_f32_e32 v234, 0x1e3ce508, v234
	v_max_f32_e32 v235, 0x1e3ce508, v235
	v_max_f32_e32 v236, 0x1e3ce508, v236
	v_max_f32_e32 v237, 0x1e3ce508, v237
	v_mul_f32_e32 v86, v86, v230
	v_mul_f32_e32 v87, v87, v231
	v_mul_f32_e32 v88, v88, v232
	v_mul_f32_e32 v89, v89, v233
	v_mul_f32_e32 v82, v82, v234
	v_mul_f32_e32 v83, v83, v235
	v_mul_f32_e32 v84, v84, v236
	v_mul_f32_e32 v85, v85, v237
	v_cvt_pk_bf16_f32 v238, v86, v87
	v_cvt_pk_bf16_f32 v239, v88, v89
	v_cvt_pk_bf16_f32 v240, v82, v83
	v_cvt_pk_bf16_f32 v241, v84, v85
	global_store_dwordx4 v132, v[238:241], s[12:13] offset:256
	s_waitcnt vmcnt(15)
	v_lshlrev_b32_e32 v230, 16, v190
	v_and_b32_e32 v231, 0xffff0000, v190
	v_lshlrev_b32_e32 v232, 16, v191
	v_and_b32_e32 v233, 0xffff0000, v191
	v_lshlrev_b32_e32 v234, 16, v192
	v_and_b32_e32 v235, 0xffff0000, v192
	v_lshlrev_b32_e32 v236, 16, v193
	v_and_b32_e32 v237, 0xffff0000, v193
	v_max_f32_e32 v230, v230, v230
	v_max_f32_e32 v231, v231, v231
	v_max_f32_e32 v232, v232, v232
	v_max_f32_e32 v233, v233, v233
	v_max_f32_e32 v234, v234, v234
	v_max_f32_e32 v235, v235, v235
	v_max_f32_e32 v236, v236, v236
	v_max_f32_e32 v237, v237, v237
	v_max_f32_e32 v230, 0x1e3ce508, v230
	v_max_f32_e32 v231, 0x1e3ce508, v231
	v_max_f32_e32 v232, 0x1e3ce508, v232
	v_max_f32_e32 v233, 0x1e3ce508, v233
	v_max_f32_e32 v234, 0x1e3ce508, v234
	v_max_f32_e32 v235, 0x1e3ce508, v235
	v_max_f32_e32 v236, 0x1e3ce508, v236
	v_max_f32_e32 v237, 0x1e3ce508, v237
	v_mul_f32_e32 v78, v78, v230
	v_mul_f32_e32 v79, v79, v231
	v_mul_f32_e32 v80, v80, v232
	v_mul_f32_e32 v81, v81, v233
	v_mul_f32_e32 v74, v74, v234
	v_mul_f32_e32 v75, v75, v235
	v_mul_f32_e32 v76, v76, v236
	v_mul_f32_e32 v77, v77, v237
	v_cvt_pk_bf16_f32 v238, v78, v79
	v_cvt_pk_bf16_f32 v239, v80, v81
	v_cvt_pk_bf16_f32 v240, v74, v75
	v_cvt_pk_bf16_f32 v241, v76, v77
	global_store_dwordx4 v133, v[238:241], s[12:13] offset:0
	s_waitcnt vmcnt(15)
; __device__ __forceinline__ unsigned cvt_pk_bf16(float lo, float hi) { unsigned r; asm volatile("v_cvt_pk_bf16_f32 %0, %1, %2" : "=v"(r) : "v"(lo), "v"(hi)); return r; }
; __device__ __forceinline__ void unpack8(u32x4 w, f32x4& lo, f32x4& hi) { lo = (f32x4){bfl(w.x), bfh(w.x), bfl(w.y), bfh(w.y)}; hi = (f32x4){bfl(w.z), bfh(w.z), bfl(w.w), bfh(w.w)}; }
;     __device__ __forceinline__ void operator()(const f32x4 (&acc)[2][2][4][2], const Unit& u, int wr, int wc, int fr, int fq) const {
;     ...
;             for (int m = 0; m < 4; ++m) { const size_t ro = (size_t)(row0 + ai * HALF + m * 16) * D + col0;
; #pragma unroll
;                 for (int bj = 0; bj < 2; ++bj) { const u32x4 bw = *(const u32x4*)(GB + ro + bj * HALF); f32x4 b0, b1; unpack8(bw, b0, b1);
;                     f32x4 v0 = acc[ai][bj][m][0], v1 = acc[ai][bj][m][1];
; #pragma unroll
;                     for (int e = 0; e < 4; ++e) { v0[e] *= fmaxf(b0[e], 1e-20f); v1[e] *= fmaxf(b1[e], 1e-20f); }
;                     u32x4 w; w.x = cvt_pk_bf16(v0[0], v0[1]); w.y = cvt_pk_bf16(v0[2], v0[3]); w.z = cvt_pk_bf16(v1[0], v1[1]); w.w = cvt_pk_bf16(v1[2], v1[3]);
;                     *(u32x4*)(MIX + ro + bj * HALF) = w; }
;                 asm volatile("" ::: "memory"); }
	v_lshlrev_b32_e32 v230, 16, v194
	v_and_b32_e32 v231, 0xffff0000, v194
	v_lshlrev_b32_e32 v232, 16, v195
	v_and_b32_e32 v233, 0xffff0000, v195
	v_lshlrev_b32_e32 v234, 16, v196
	v_and_b32_e32 v235, 0xffff0000, v196
	v_lshlrev_b32_e32 v236, 16, v197
	v_and_b32_e32 v237, 0xffff0000, v197
	v_max_f32_e32 v230, v230, v230
	v_max_f32_e32 v231, v231, v231
	v_max_f32_e32 v232, v232, v232
	v_max_f32_e32 v233, v233, v233
	v_max_f32_e32 v234, v234, v234
	v_max_f32_e32 v235, v235, v235
	v_max_f32_e32 v236, v236, v236
	v_max_f32_e32 v237, v237, v237
	v_max_f32_e32 v230, 0x1e3ce508, v230
	v_max_f32_e32 v231, 0x1e3ce508, v231
	v_max_f32_e32 v232, 0x1e3ce508, v232
	v_max_f32_e32 v233, 0x1e3ce508, v233
	v_max_f32_e32 v234, 0x1e3ce508, v234
	v_max_f32_e32 v235, 0x1e3ce508, v235
	v_max_f32_e32 v236, 0x1e3ce508, v236
	v_max_f32_e32 v237, 0x1e3ce508, v237
	v_mul_f32_e32 v70, v70, v230
	v_mul_f32_e32 v71, v71, v231
	v_mul_f32_e32 v72, v72, v232
	v_mul_f32_e32 v73, v73, v233
	v_mul_f32_e32 v66, v66, v234
	v_mul_f32_e32 v67, v67, v235
	v_mul_f32_e32 v68, v68, v236
	v_mul_f32_e32 v69, v69, v237
	v_cvt_pk_bf16_f32 v238, v70, v71
	v_cvt_pk_bf16_f32 v239, v72, v73
	v_cvt_pk_bf16_f32 v240, v66, v67
	v_cvt_pk_bf16_f32 v241, v68, v69
	global_store_dwordx4 v133, v[238:241], s[12:13] offset:256
	s_waitcnt vmcnt(15)
	v_lshlrev_b32_e32 v230, 16, v198
	v_and_b32_e32 v231, 0xffff0000, v198
	v_lshlrev_b32_e32 v232, 16, v199
	v_and_b32_e32 v233, 0xffff0000, v199
	v_lshlrev_b32_e32 v234, 16, v200
	v_and_b32_e32 v235, 0xffff0000, v200
	v_lshlrev_b32_e32 v236, 16, v201
	v_and_b32_e32 v237, 0xffff0000, v201
	v_max_f32_e32 v230, v230, v230
	v_max_f32_e32 v231, v231, v231
	v_max_f32_e32 v232, v232, v232
	v_max_f32_e32 v233, v233, v233
	v_max_f32_e32 v234, v234, v234
	v_max_f32_e32 v235, v235, v235
	v_max_f32_e32 v236, v236, v236
	v_max_f32_e32 v237, v237, v237
	v_max_f32_e32 v230, 0x1e3ce508, v230
	v_max_f32_e32 v231, 0x1e3ce508, v231
	v_max_f32_e32 v232, 0x1e3ce508, v232
	v_max_f32_e32 v233, 0x1e3ce508, v233
	v_max_f32_e32 v234, 0x1e3ce508, v234
	v_max_f32_e32 v235, 0x1e3ce508, v235
	v_max_f32_e32 v236, 0x1e3ce508, v236
	v_max_f32_e32 v237, 0x1e3ce508, v237
	v_mul_f32_e32 v62, v62, v230
	v_mul_f32_e32 v63, v63, v231
	v_mul_f32_e32 v64, v64, v232
	v_mul_f32_e32 v65, v65, v233
	v_mul_f32_e32 v58, v58, v234
	v_mul_f32_e32 v59, v59, v235
	v_mul_f32_e32 v60, v60, v236
	v_mul_f32_e32 v61, v61, v237
	v_cvt_pk_bf16_f32 v238, v62, v63
	v_cvt_pk_bf16_f32 v239, v64, v65
	v_cvt_pk_bf16_f32 v240, v58, v59
	v_cvt_pk_bf16_f32 v241, v60, v61
	global_store_dwordx4 v134, v[238:241], s[12:13] offset:0
	s_waitcnt vmcnt(15)
	v_lshlrev_b32_e32 v230, 16, v202
	v_and_b32_e32 v231, 0xffff0000, v202
	v_lshlrev_b32_e32 v232, 16, v203
	v_and_b32_e32 v233, 0xffff0000, v203
	v_lshlrev_b32_e32 v234, 16, v204
	v_and_b32_e32 v235, 0xffff0000, v204
	v_lshlrev_b32_e32 v236, 16, v205
	v_and_b32_e32 v237, 0xffff0000, v205
	v_max_f32_e32 v230, v230, v230
	v_max_f32_e32 v231, v231, v231
	v_max_f32_e32 v232, v232, v232
	v_max_f32_e32 v233, v233, v233
	v_max_f32_e32 v234, v234, v234
	v_max_f32_e32 v235, v235, v235
	v_max_f32_e32 v236, v236, v236
	v_max_f32_e32 v237, v237, v237
	v_max_f32_e32 v230, 0x1e3ce508, v230
	v_max_f32_e32 v231, 0x1e3ce508, v231
	v_max_f32_e32 v232, 0x1e3ce508, v232
	v_max_f32_e32 v233, 0x1e3ce508, v233
	v_max_f32_e32 v234, 0x1e3ce508, v234
	v_max_f32_e32 v235, 0x1e3ce508, v235
	v_max_f32_e32 v236, 0x1e3ce508, v236
	v_max_f32_e32 v237, 0x1e3ce508, v237
	v_mul_f32_e32 v54, v54, v230
	v_mul_f32_e32 v55, v55, v231
	v_mul_f32_e32 v56, v56, v232
	v_mul_f32_e32 v57, v57, v233
	v_mul_f32_e32 v50, v50, v234
	v_mul_f32_e32 v51, v51, v235
	v_mul_f32_e32 v52, v52, v236
	v_mul_f32_e32 v53, v53, v237
	v_cvt_pk_bf16_f32 v238, v54, v55
	v_cvt_pk_bf16_f32 v239, v56, v57
	v_cvt_pk_bf16_f32 v240, v50, v51
	v_cvt_pk_bf16_f32 v241, v52, v53
	global_store_dwordx4 v134, v[238:241], s[12:13] offset:256
	s_waitcnt vmcnt(15)
	v_lshlrev_b32_e32 v230, 16, v206
	v_and_b32_e32 v231, 0xffff0000, v206
	v_lshlrev_b32_e32 v232, 16, v207
	v_and_b32_e32 v233, 0xffff0000, v207
	v_lshlrev_b32_e32 v234, 16, v208
	v_and_b32_e32 v235, 0xffff0000, v208
	v_lshlrev_b32_e32 v236, 16, v209
	v_and_b32_e32 v237, 0xffff0000, v209
	v_max_f32_e32 v230, v230, v230
	v_max_f32_e32 v231, v231, v231
	v_max_f32_e32 v232, v232, v232
	v_max_f32_e32 v233, v233, v233
	v_max_f32_e32 v234, v234, v234
	v_max_f32_e32 v235, v235, v235
	v_max_f32_e32 v236, v236, v236
	v_max_f32_e32 v237, v237, v237
	v_max_f32_e32 v230, 0x1e3ce508, v230
	v_max_f32_e32 v231, 0x1e3ce508, v231
	v_max_f32_e32 v232, 0x1e3ce508, v232
	v_max_f32_e32 v233, 0x1e3ce508, v233
	v_max_f32_e32 v234, 0x1e3ce508, v234
	v_max_f32_e32 v235, 0x1e3ce508, v235
	v_max_f32_e32 v236, 0x1e3ce508, v236
	v_max_f32_e32 v237, 0x1e3ce508, v237
	v_mul_f32_e32 v46, v46, v230
	v_mul_f32_e32 v47, v47, v231
	v_mul_f32_e32 v48, v48, v232
	v_mul_f32_e32 v49, v49, v233
	v_mul_f32_e32 v42, v42, v234
	v_mul_f32_e32 v43, v43, v235
	v_mul_f32_e32 v44, v44, v236
	v_mul_f32_e32 v45, v45, v237
	v_cvt_pk_bf16_f32 v238, v46, v47
	v_cvt_pk_bf16_f32 v239, v48, v49
	v_cvt_pk_bf16_f32 v240, v42, v43
	v_cvt_pk_bf16_f32 v241, v44, v45
	global_store_dwordx4 v135, v[238:241], s[12:13] offset:0
	s_waitcnt vmcnt(15)
; __device__ __forceinline__ unsigned cvt_pk_bf16(float lo, float hi) { unsigned r; asm volatile("v_cvt_pk_bf16_f32 %0, %1, %2" : "=v"(r) : "v"(lo), "v"(hi)); return r; }
; __device__ __forceinline__ void unpack8(u32x4 w, f32x4& lo, f32x4& hi) { lo = (f32x4){bfl(w.x), bfh(w.x), bfl(w.y), bfh(w.y)}; hi = (f32x4){bfl(w.z), bfh(w.z), bfl(w.w), bfh(w.w)}; }
;     __device__ __forceinline__ void operator()(const f32x4 (&acc)[2][2][4][2], const Unit& u, int wr, int wc, int fr, int fq) const {
;     ...
;             for (int m = 0; m < 4; ++m) { const size_t ro = (size_t)(row0 + ai * HALF + m * 16) * D + col0;
; #pragma unroll
;                 for (int bj = 0; bj < 2; ++bj) { const u32x4 bw = *(const u32x4*)(GB + ro + bj * HALF); f32x4 b0, b1; unpack8(bw, b0, b1);
;                     f32x4 v0 = acc[ai][bj][m][0], v1 = acc[ai][bj][m][1];
; #pragma unroll
;                     for (int e = 0; e < 4; ++e) { v0[e] *= fmaxf(b0[e], 1e-20f); v1[e] *= fmaxf(b1[e], 1e-20f); }
;                     u32x4 w; w.x = cvt_pk_bf16(v0[0], v0[1]); w.y = cvt_pk_bf16(v0[2], v0[3]); w.z = cvt_pk_bf16(v1[0], v1[1]); w.w = cvt_pk_bf16(v1[2], v1[3]);
;                     *(u32x4*)(MIX + ro + bj * HALF) = w; }
;                 asm volatile("" ::: "memory"); }
	v_lshlrev_b32_e32 v230, 16, v210
	v_and_b32_e32 v231, 0xffff0000, v210
	v_lshlrev_b32_e32 v232, 16, v211
	v_and_b32_e32 v233, 0xffff0000, v211
	v_lshlrev_b32_e32 v234, 16, v212
	v_and_b32_e32 v235, 0xffff0000, v212
	v_lshlrev_b32_e32 v236, 16, v213
	v_and_b32_e32 v237, 0xffff0000, v213
	v_max_f32_e32 v230, v230, v230
	v_max_f32_e32 v231, v231, v231
	v_max_f32_e32 v232, v232, v232
	v_max_f32_e32 v233, v233, v233
	v_max_f32_e32 v234, v234, v234
	v_max_f32_e32 v235, v235, v235
	v_max_f32_e32 v236, v236, v236
	v_max_f32_e32 v237, v237, v237
	v_max_f32_e32 v230, 0x1e3ce508, v230
	v_max_f32_e32 v231, 0x1e3ce508, v231
	v_max_f32_e32 v232, 0x1e3ce508, v232
	v_max_f32_e32 v233, 0x1e3ce508, v233
	v_max_f32_e32 v234, 0x1e3ce508, v234
	v_max_f32_e32 v235, 0x1e3ce508, v235
	v_max_f32_e32 v236, 0x1e3ce508, v236
	v_max_f32_e32 v237, 0x1e3ce508, v237
	v_mul_f32_e32 v38, v38, v230
	v_mul_f32_e32 v39, v39, v231
	v_mul_f32_e32 v40, v40, v232
	v_mul_f32_e32 v41, v41, v233
	v_mul_f32_e32 v34, v34, v234
	v_mul_f32_e32 v35, v35, v235
	v_mul_f32_e32 v36, v36, v236
	v_mul_f32_e32 v37, v37, v237
	v_cvt_pk_bf16_f32 v238, v38, v39
	v_cvt_pk_bf16_f32 v239, v40, v41
	v_cvt_pk_bf16_f32 v240, v34, v35
	v_cvt_pk_bf16_f32 v241, v36, v37
	global_store_dwordx4 v135, v[238:241], s[12:13] offset:256
	s_waitcnt vmcnt(15)
	v_lshlrev_b32_e32 v230, 16, v214
	v_and_b32_e32 v231, 0xffff0000, v214
	v_lshlrev_b32_e32 v232, 16, v215
	v_and_b32_e32 v233, 0xffff0000, v215
	v_lshlrev_b32_e32 v234, 16, v216
	v_and_b32_e32 v235, 0xffff0000, v216
	v_lshlrev_b32_e32 v236, 16, v217
	v_and_b32_e32 v237, 0xffff0000, v217
	v_max_f32_e32 v230, v230, v230
	v_max_f32_e32 v231, v231, v231
	v_max_f32_e32 v232, v232, v232
	v_max_f32_e32 v233, v233, v233
	v_max_f32_e32 v234, v234, v234
	v_max_f32_e32 v235, v235, v235
	v_max_f32_e32 v236, v236, v236
	v_max_f32_e32 v237, v237, v237
	v_max_f32_e32 v230, 0x1e3ce508, v230
	v_max_f32_e32 v231, 0x1e3ce508, v231
	v_max_f32_e32 v232, 0x1e3ce508, v232
	v_max_f32_e32 v233, 0x1e3ce508, v233
	v_max_f32_e32 v234, 0x1e3ce508, v234
	v_max_f32_e32 v235, 0x1e3ce508, v235
	v_max_f32_e32 v236, 0x1e3ce508, v236
	v_max_f32_e32 v237, 0x1e3ce508, v237
	v_mul_f32_e32 v30, v30, v230
	v_mul_f32_e32 v31, v31, v231
	v_mul_f32_e32 v32, v32, v232
	v_mul_f32_e32 v33, v33, v233
	v_mul_f32_e32 v26, v26, v234
	v_mul_f32_e32 v27, v27, v235
	v_mul_f32_e32 v28, v28, v236
	v_mul_f32_e32 v29, v29, v237
	v_cvt_pk_bf16_f32 v238, v30, v31
	v_cvt_pk_bf16_f32 v239, v32, v33
	v_cvt_pk_bf16_f32 v240, v26, v27
	v_cvt_pk_bf16_f32 v241, v28, v29
	global_store_dwordx4 v136, v[238:241], s[12:13] offset:0
	s_waitcnt vmcnt(15)
	v_lshlrev_b32_e32 v230, 16, v218
	v_and_b32_e32 v231, 0xffff0000, v218
	v_lshlrev_b32_e32 v232, 16, v219
	v_and_b32_e32 v233, 0xffff0000, v219
	v_lshlrev_b32_e32 v234, 16, v220
	v_and_b32_e32 v235, 0xffff0000, v220
	v_lshlrev_b32_e32 v236, 16, v221
	v_and_b32_e32 v237, 0xffff0000, v221
	v_max_f32_e32 v230, v230, v230
	v_max_f32_e32 v231, v231, v231
	v_max_f32_e32 v232, v232, v232
	v_max_f32_e32 v233, v233, v233
	v_max_f32_e32 v234, v234, v234
	v_max_f32_e32 v235, v235, v235
	v_max_f32_e32 v236, v236, v236
	v_max_f32_e32 v237, v237, v237
	v_max_f32_e32 v230, 0x1e3ce508, v230
	v_max_f32_e32 v231, 0x1e3ce508, v231
	v_max_f32_e32 v232, 0x1e3ce508, v232
	v_max_f32_e32 v233, 0x1e3ce508, v233
	v_max_f32_e32 v234, 0x1e3ce508, v234
	v_max_f32_e32 v235, 0x1e3ce508, v235
	v_max_f32_e32 v236, 0x1e3ce508, v236
	v_max_f32_e32 v237, 0x1e3ce508, v237
	v_mul_f32_e32 v22, v22, v230
	v_mul_f32_e32 v23, v23, v231
	v_mul_f32_e32 v24, v24, v232
	v_mul_f32_e32 v25, v25, v233
	v_mul_f32_e32 v18, v18, v234
	v_mul_f32_e32 v19, v19, v235
	v_mul_f32_e32 v20, v20, v236
	v_mul_f32_e32 v21, v21, v237
	v_cvt_pk_bf16_f32 v238, v22, v23
	v_cvt_pk_bf16_f32 v239, v24, v25
	v_cvt_pk_bf16_f32 v240, v18, v19
	v_cvt_pk_bf16_f32 v241, v20, v21
	global_store_dwordx4 v136, v[238:241], s[12:13] offset:256
	s_waitcnt vmcnt(15)
	v_lshlrev_b32_e32 v230, 16, v222
	v_and_b32_e32 v231, 0xffff0000, v222
	v_lshlrev_b32_e32 v232, 16, v223
	v_and_b32_e32 v233, 0xffff0000, v223
	v_lshlrev_b32_e32 v234, 16, v224
	v_and_b32_e32 v235, 0xffff0000, v224
	v_lshlrev_b32_e32 v236, 16, v225
	v_and_b32_e32 v237, 0xffff0000, v225
	v_max_f32_e32 v230, v230, v230
	v_max_f32_e32 v231, v231, v231
	v_max_f32_e32 v232, v232, v232
	v_max_f32_e32 v233, v233, v233
	v_max_f32_e32 v234, v234, v234
	v_max_f32_e32 v235, v235, v235
	v_max_f32_e32 v236, v236, v236
	v_max_f32_e32 v237, v237, v237
	v_max_f32_e32 v230, 0x1e3ce508, v230
	v_max_f32_e32 v231, 0x1e3ce508, v231
	v_max_f32_e32 v232, 0x1e3ce508, v232
	v_max_f32_e32 v233, 0x1e3ce508, v233
	v_max_f32_e32 v234, 0x1e3ce508, v234
	v_max_f32_e32 v235, 0x1e3ce508, v235
	v_max_f32_e32 v236, 0x1e3ce508, v236
	v_max_f32_e32 v237, 0x1e3ce508, v237
	v_mul_f32_e32 v14, v14, v230
	v_mul_f32_e32 v15, v15, v231
	v_mul_f32_e32 v16, v16, v232
	v_mul_f32_e32 v17, v17, v233
	v_mul_f32_e32 v10, v10, v234
	v_mul_f32_e32 v11, v11, v235
	v_mul_f32_e32 v12, v12, v236
	v_mul_f32_e32 v13, v13, v237
	v_cvt_pk_bf16_f32 v238, v14, v15
	v_cvt_pk_bf16_f32 v239, v16, v17
	v_cvt_pk_bf16_f32 v240, v10, v11
	v_cvt_pk_bf16_f32 v241, v12, v13
	global_store_dwordx4 v137, v[238:241], s[12:13] offset:0
	s_waitcnt vmcnt(15)
	v_lshlrev_b32_e32 v230, 16, v226
	v_and_b32_e32 v231, 0xffff0000, v226
	v_lshlrev_b32_e32 v232, 16, v227
	v_and_b32_e32 v233, 0xffff0000, v227
	v_lshlrev_b32_e32 v234, 16, v228
	v_and_b32_e32 v235, 0xffff0000, v228
	v_lshlrev_b32_e32 v236, 16, v229
	v_and_b32_e32 v237, 0xffff0000, v229
	v_max_f32_e32 v230, v230, v230
	v_max_f32_e32 v231, v231, v231
	v_max_f32_e32 v232, v232, v232
	v_max_f32_e32 v233, v233, v233
	v_max_f32_e32 v234, v234, v234
	v_max_f32_e32 v235, v235, v235
	v_max_f32_e32 v236, v236, v236
	v_max_f32_e32 v237, v237, v237
	v_max_f32_e32 v230, 0x1e3ce508, v230
	v_max_f32_e32 v231, 0x1e3ce508, v231
	v_max_f32_e32 v232, 0x1e3ce508, v232
	v_max_f32_e32 v233, 0x1e3ce508, v233
	v_max_f32_e32 v234, 0x1e3ce508, v234
	v_max_f32_e32 v235, 0x1e3ce508, v235
	v_max_f32_e32 v236, 0x1e3ce508, v236
	v_max_f32_e32 v237, 0x1e3ce508, v237
	v_mul_f32_e32 v6, v6, v230
	v_mul_f32_e32 v7, v7, v231
	v_mul_f32_e32 v8, v8, v232
	v_mul_f32_e32 v9, v9, v233
	v_mul_f32_e32 v2, v2, v234
	v_mul_f32_e32 v3, v3, v235
	v_mul_f32_e32 v4, v4, v236
	v_mul_f32_e32 v5, v5, v237
	v_cvt_pk_bf16_f32 v238, v6, v7
	v_cvt_pk_bf16_f32 v239, v8, v9
	v_cvt_pk_bf16_f32 v240, v2, v3
	v_cvt_pk_bf16_f32 v241, v4, v5
	global_store_dwordx4 v137, v[238:241], s[12:13] offset:256
	s_mov_b64 s[28:29], 0xb0000
	s_cbranch_vccnz .LBB0_1191
	s_andn2_b64 vcc, exec, s[10:11]
	s_cbranch_vccnz .LBB0_1190
	s_barrier
	s_branch .LBB0_1190
